# grid barrier: L1 invalidate issued at arrival (overlaps arrive atomic) instead of after release; plus PRO deferred gain
# speedup vs baseline: 1.0232x; 1.0134x over previous
.LBB0_688:
	s_or_b32 s2, s3, 1
	s_cmp_lt_i32 s2, s33
	s_cselect_b64 s[14:15], -1, 0
	s_add_i32 s11, s11, 1
	s_cmp_lt_i32 s11, s73
	s_cselect_b64 s[16:17], -1, 0
	s_and_b64 s[14:15], s[14:15], s[16:17]
	s_andn2_b64 vcc, exec, s[14:15]
	s_cbranch_vccnz .LBB0_9
	s_and_b64 vcc, exec, s[96:97]
	s_cbranch_vccz .LBB0_702
	v_readlane_b32 s14, v254, 2
	v_readlane_b32 s15, v254, 3
	s_mov_b64 s[24:25], 0
	s_and_b64 vcc, exec, s[14:15]
	s_mov_b64 s[26:27], 0
	s_cbranch_vccz .LBB0_703
	s_waitcnt vmcnt(0)
	v_cmp_eq_u32_e32 vcc, 0, v208
	s_waitcnt vmcnt(0) lgkmcnt(0)
	s_barrier
	s_and_saveexec_b64 s[26:27], vcc
	s_cbranch_execz .LBB0_742
	v_readlane_b32 s2, v255, 12
	s_waitcnt vmcnt(0) expcnt(0) lgkmcnt(0)
	buffer_inv sc1
	s_nop 0
	v_mov_b32_e32 v0, s2
	ds_read_b32 v3, v0
	v_readlane_b32 s2, v255, 13
	s_waitcnt lgkmcnt(0)
	v_cmp_ne_u32_e32 vcc, 0, v3
	v_mov_b32_e32 v0, s2
	ds_read_b32 v2, v0
	s_cbranch_vccnz .LBB0_710
	s_mov_b32 s2, 1
	s_branch .LBB0_695

.LBB0_723:
	s_or_b64 exec, exec, s[30:31]
	s_waitcnt vmcnt(0)
	s_waitcnt vmcnt(0)

.LBB0_741:
	s_or_b64 exec, exec, s[28:29]
	v_readlane_b32 s12, v255, 6
	v_readlane_b32 s13, v255, 7
	s_waitcnt vmcnt(0)
	s_nop 2
	global_atomic_add v1, v233, s[12:13]
	s_waitcnt vmcnt(0)
